# nt (streaming) hint on the in-loop residual tile loads (read-once data)
# speedup vs baseline: 1.0470x; 1.0470x over previous
.Lrk_344:
	s_add_i32 vcc_lo, s50, 2
	s_add_u32 s68, s48, 0x80
	s_addc_u32 s51, s49, 0
	s_add_i32 s70, 0, 0x10000
	s_cmp_eq_u32 s15, s50
	s_cselect_b32 s51, s1, s51
	s_cselect_b32 s50, s0, s68
	v_add_u32_e32 v0, s70, v223
	s_cselect_b32 s69, s53, s57
	s_cselect_b32 s68, s52, s56
	s_add_i32 s71, 0, 0x14000
	ds_read_b128 v[130:133], v0
	ds_read_b128 v[134:137], v0 offset:1024
	ds_read_b128 v[138:141], v0 offset:2048
	ds_read_b128 v[142:145], v0 offset:3072
	v_add_u32_e32 v0, s71, v223
	ds_read_b128 v[146:149], v0
	ds_read_b128 v[150:153], v0 offset:1024
	ds_read_b128 v[154:157], v0 offset:2048
	ds_read_b128 v[158:161], v0 offset:3072
	s_add_i32 s98, vcc_lo, -2
	s_lshr_b32 s99, s98, 3
	s_lshl_b32 s99, s99, 17
	s_and_b32 vcc_hi, s98, 2
	s_lshl_b32 vcc_hi, vcc_hi, 5
	s_or_b32 s99, s99, vcc_hi
	s_and_b32 vcc_hi, s98, 4
	s_lshl_b32 vcc_hi, vcc_hi, 7
	s_or_b32 s98, s99, vcc_hi
	s_add_u32 s98, s100, s98
	s_addc_u32 s99, s101, 0
	s_nop 0
	global_load_dwordx4 v[240:243], v238, s[98:99] nt
	v_lshl_add_u64 v[212:213], s[48:49], 0, v[192:193]
	s_add_i32 m0, s67, 0xc000
	ds_read_b128 v[162:165], v226
	ds_read_b128 v[166:169], v226 offset:1024
	ds_read_b128 v[170:173], v226 offset:2048
	ds_read_b128 v[174:177], v226 offset:3072
	ds_read_b128 v[196:199], v226 offset:4096
	ds_read_b128 v[200:203], v226 offset:5120
	ds_read_b128 v[204:207], v226 offset:6144
	ds_read_b128 v[208:211], v226 offset:7168
	global_load_lds_dwordx4 v[212:213], off
	v_lshl_add_u64 v[212:213], s[48:49], 0, v[194:195]
	s_add_i32 m0, s67, 0xe000
	s_nop 0
	global_load_lds_dwordx4 v[212:213], off
	s_waitcnt vmcnt(9)
	s_waitcnt lgkmcnt(0)
	s_barrier
	s_setprio 1
	s_waitcnt lgkmcnt(0)
	v_mfma_f32_16x16x32_bf16 v[126:129], v[130:133], v[162:165], v[126:129]
	v_mfma_f32_16x16x32_bf16 v[122:125], v[138:141], v[162:165], v[122:125]
	v_mfma_f32_16x16x32_bf16 v[118:121], v[130:133], v[170:173], v[118:121]
	v_mfma_f32_16x16x32_bf16 v[114:117], v[138:141], v[170:173], v[114:117]
	v_mfma_f32_16x16x32_bf16 v[102:105], v[130:133], v[196:199], v[102:105]
	v_mfma_f32_16x16x32_bf16 v[98:101], v[138:141], v[196:199], v[98:101]
	v_mfma_f32_16x16x32_bf16 v[86:89], v[130:133], v[204:207], v[86:89]
	v_mfma_f32_16x16x32_bf16 v[82:85], v[138:141], v[204:207], v[82:85]
	v_mfma_f32_16x16x32_bf16 v[126:129], v[134:137], v[166:169], v[126:129]
	v_mfma_f32_16x16x32_bf16 v[122:125], v[142:145], v[166:169], v[122:125]
	v_mfma_f32_16x16x32_bf16 v[118:121], v[134:137], v[174:177], v[118:121]
	v_mfma_f32_16x16x32_bf16 v[114:117], v[142:145], v[174:177], v[114:117]
	v_mfma_f32_16x16x32_bf16 v[102:105], v[134:137], v[200:203], v[102:105]
	v_mfma_f32_16x16x32_bf16 v[98:101], v[142:145], v[200:203], v[98:101]
	v_mfma_f32_16x16x32_bf16 v[86:89], v[134:137], v[208:211], v[86:89]
	v_mfma_f32_16x16x32_bf16 v[82:85], v[142:145], v[208:211], v[82:85]
	s_setprio 0
	s_setprio 1
	v_mfma_f32_16x16x32_bf16 v[110:113], v[146:149], v[162:165], v[110:113]
	v_mfma_f32_16x16x32_bf16 v[106:109], v[154:157], v[162:165], v[106:109]
	v_mfma_f32_16x16x32_bf16 v[94:97], v[146:149], v[170:173], v[94:97]
	v_mfma_f32_16x16x32_bf16 v[90:93], v[154:157], v[170:173], v[90:93]
	v_mfma_f32_16x16x32_bf16 v[78:81], v[146:149], v[196:199], v[78:81]
	v_mfma_f32_16x16x32_bf16 v[74:77], v[154:157], v[196:199], v[74:77]
	v_mfma_f32_16x16x32_bf16 v[70:73], v[146:149], v[204:207], v[70:73]
	v_mfma_f32_16x16x32_bf16 v[66:69], v[154:157], v[204:207], v[66:69]
	v_mfma_f32_16x16x32_bf16 v[110:113], v[150:153], v[166:169], v[110:113]
	v_mfma_f32_16x16x32_bf16 v[106:109], v[158:161], v[166:169], v[106:109]
	v_mfma_f32_16x16x32_bf16 v[94:97], v[150:153], v[174:177], v[94:97]
	v_mfma_f32_16x16x32_bf16 v[90:93], v[158:161], v[174:177], v[90:93]
	v_mfma_f32_16x16x32_bf16 v[78:81], v[150:153], v[200:203], v[78:81]
	v_mfma_f32_16x16x32_bf16 v[74:77], v[158:161], v[200:203], v[74:77]
	v_mfma_f32_16x16x32_bf16 v[70:73], v[150:153], v[208:211], v[70:73]
	v_mfma_f32_16x16x32_bf16 v[66:69], v[158:161], v[208:211], v[66:69]
	s_setprio 0
	s_barrier
	s_add_i32 s70, s70, s63
	v_lshl_add_u64 v[212:213], s[68:69], 0, v[186:187]
	s_mov_b32 m0, s70
	ds_read_b128 v[162:165], v226 offset:16384
	ds_read_b128 v[166:169], v226 offset:17408
	ds_read_b128 v[170:173], v226 offset:18432
	ds_read_b128 v[174:177], v226 offset:19456
	ds_read_b128 v[196:199], v226 offset:20480
	ds_read_b128 v[200:203], v226 offset:21504
	ds_read_b128 v[204:207], v226 offset:22528
	ds_read_b128 v[208:211], v226 offset:23552
	global_load_lds_dwordx4 v[212:213], off
	s_add_i32 m0, s70, 0x2000
	v_lshl_add_u64 v[214:215], s[68:69], 0, v[182:183]
	s_add_u32 s68, s68, s90
	s_addc_u32 s69, s69, 0
	s_add_i32 s70, s71, s63
	global_load_lds_dwordx4 v[214:215], off
	v_lshl_add_u64 v[216:217], s[68:69], 0, v[186:187]
	s_mov_b32 m0, s70
	v_lshl_add_u64 v[218:219], s[68:69], 0, v[182:183]
	global_load_lds_dwordx4 v[216:217], off
	s_add_i32 m0, s70, 0x2000
	v_lshl_add_u64 v[232:233], s[50:51], 0, v[184:185]
	global_load_lds_dwordx4 v[218:219], off
	s_mov_b32 m0, s67
	v_lshl_add_u64 v[234:235], s[50:51], 0, v[180:181]
	global_load_lds_dwordx4 v[232:233], off
	s_mov_b32 m0, s33
	s_nop 0
	global_load_lds_dwordx4 v[234:235], off
	s_waitcnt vmcnt(8)
	s_add_i32 s98, vcc_lo, -2
	s_cmp_lt_u32 s98, 16
	s_cbranch_scc0 .Lrk_dU_8_16
	s_cmp_lt_u32 s98, 8
	s_cbranch_scc0 .Lrk_dU_4_8
	s_cmp_lt_u32 s98, 4
	s_cbranch_scc0 .Lrk_dU_2_4
	s_cmp_lt_u32 s98, 2
	s_cbranch_scc0 .Lrk_dU_1_2
	v_pk_add_f32 v[126:127], v[126:127], v[240:241]
	v_pk_add_f32 v[128:129], v[128:129], v[242:243]
	s_branch .Lrk_joinU

.Lrk_joinU:
	s_waitcnt lgkmcnt(0)
	s_barrier
	s_setprio 1
	s_waitcnt lgkmcnt(0)
	v_mfma_f32_16x16x32_bf16 v[62:65], v[130:133], v[162:165], v[62:65]
	v_mfma_f32_16x16x32_bf16 v[58:61], v[138:141], v[162:165], v[58:61]
	v_mfma_f32_16x16x32_bf16 v[54:57], v[130:133], v[170:173], v[54:57]
	v_mfma_f32_16x16x32_bf16 v[50:53], v[138:141], v[170:173], v[50:53]
	v_mfma_f32_16x16x32_bf16 v[38:41], v[130:133], v[196:199], v[38:41]
	v_mfma_f32_16x16x32_bf16 v[34:37], v[138:141], v[196:199], v[34:37]
	v_mfma_f32_16x16x32_bf16 v[22:25], v[130:133], v[204:207], v[22:25]
	v_mfma_f32_16x16x32_bf16 v[18:21], v[138:141], v[204:207], v[18:21]
	v_mfma_f32_16x16x32_bf16 v[62:65], v[134:137], v[166:169], v[62:65]
	v_mfma_f32_16x16x32_bf16 v[58:61], v[142:145], v[166:169], v[58:61]
	v_mfma_f32_16x16x32_bf16 v[54:57], v[134:137], v[174:177], v[54:57]
	v_mfma_f32_16x16x32_bf16 v[50:53], v[142:145], v[174:177], v[50:53]
	v_mfma_f32_16x16x32_bf16 v[38:41], v[134:137], v[200:203], v[38:41]
	v_mfma_f32_16x16x32_bf16 v[34:37], v[142:145], v[200:203], v[34:37]
	v_mfma_f32_16x16x32_bf16 v[22:25], v[134:137], v[208:211], v[22:25]
	v_mfma_f32_16x16x32_bf16 v[18:21], v[142:145], v[208:211], v[18:21]
	s_setprio 0
	s_setprio 1
	v_mfma_f32_16x16x32_bf16 v[46:49], v[146:149], v[162:165], v[46:49]
	v_mfma_f32_16x16x32_bf16 v[42:45], v[154:157], v[162:165], v[42:45]
	v_mfma_f32_16x16x32_bf16 v[30:33], v[146:149], v[170:173], v[30:33]
	v_mfma_f32_16x16x32_bf16 v[26:29], v[154:157], v[170:173], v[26:29]
	v_mfma_f32_16x16x32_bf16 v[14:17], v[146:149], v[196:199], v[14:17]
	v_mfma_f32_16x16x32_bf16 v[10:13], v[154:157], v[196:199], v[10:13]
	v_mfma_f32_16x16x32_bf16 v[6:9], v[146:149], v[204:207], v[6:9]
	v_mfma_f32_16x16x32_bf16 v[2:5], v[154:157], v[204:207], v[2:5]
	v_mfma_f32_16x16x32_bf16 v[46:49], v[150:153], v[166:169], v[46:49]
	v_mfma_f32_16x16x32_bf16 v[42:45], v[158:161], v[166:169], v[42:45]
	v_mfma_f32_16x16x32_bf16 v[30:33], v[150:153], v[174:177], v[30:33]
	v_mfma_f32_16x16x32_bf16 v[26:29], v[158:161], v[174:177], v[26:29]
	v_mfma_f32_16x16x32_bf16 v[14:17], v[150:153], v[200:203], v[14:17]
	v_mfma_f32_16x16x32_bf16 v[10:13], v[158:161], v[200:203], v[10:13]
	v_mfma_f32_16x16x32_bf16 v[6:9], v[150:153], v[208:211], v[6:9]
	v_mfma_f32_16x16x32_bf16 v[2:5], v[158:161], v[208:211], v[2:5]
	s_setprio 0
	s_barrier
	s_add_i32 s68, 0, 0x18000
	v_add_u32_e32 v0, s68, v223
	s_add_i32 s69, 0, 0x1c000
	ds_read_b128 v[130:133], v0
	ds_read_b128 v[134:137], v0 offset:1024
	ds_read_b128 v[138:141], v0 offset:2048
	ds_read_b128 v[142:145], v0 offset:3072
	v_add_u32_e32 v0, s69, v223
	ds_read_b128 v[146:149], v0
	ds_read_b128 v[150:153], v0 offset:1024
	ds_read_b128 v[154:157], v0 offset:2048
	ds_read_b128 v[158:161], v0 offset:3072
	s_add_u32 s50, s50, s90
	s_addc_u32 s51, s51, 0
	s_mov_b32 m0, s65
	s_add_i32 s98, vcc_lo, -2
	s_lshr_b32 s99, s98, 3
	s_lshl_b32 s99, s99, 17
	s_and_b32 vcc_hi, s98, 2
	s_lshl_b32 vcc_hi, vcc_hi, 5
	s_or_b32 s99, s99, vcc_hi
	s_and_b32 vcc_hi, s98, 4
	s_lshl_b32 vcc_hi, vcc_hi, 7
	s_or_b32 s98, s99, vcc_hi
	s_add_u32 s98, s98, 0x100000
	s_add_u32 s98, s100, s98
	s_addc_u32 s99, s101, 0
	s_nop 0
	global_load_dwordx4 v[240:243], v238, s[98:99] nt
	v_lshl_add_u64 v[236:237], s[50:51], 0, v[184:185]
	ds_read_b128 v[162:165], v226 offset:32768
	ds_read_b128 v[166:169], v226 offset:33792
	ds_read_b128 v[170:173], v226 offset:34816
	ds_read_b128 v[174:177], v226 offset:35840
	ds_read_b128 v[196:199], v226 offset:36864
	ds_read_b128 v[200:203], v226 offset:37888
	ds_read_b128 v[204:207], v226 offset:38912
	ds_read_b128 v[208:211], v226 offset:39936
	global_load_lds_dwordx4 v[236:237], off
	v_lshl_add_u64 v[236:237], s[50:51], 0, v[180:181]
	s_mov_b32 m0, s22
	s_nop 0
	global_load_lds_dwordx4 v[236:237], off
	s_waitcnt vmcnt(9)
	s_waitcnt lgkmcnt(0)
	s_barrier
	s_setprio 1
	s_waitcnt lgkmcnt(0)
	v_mfma_f32_16x16x32_bf16 v[126:129], v[130:133], v[162:165], v[126:129]
	v_mfma_f32_16x16x32_bf16 v[122:125], v[138:141], v[162:165], v[122:125]
	v_mfma_f32_16x16x32_bf16 v[118:121], v[130:133], v[170:173], v[118:121]
	v_mfma_f32_16x16x32_bf16 v[114:117], v[138:141], v[170:173], v[114:117]
	v_mfma_f32_16x16x32_bf16 v[102:105], v[130:133], v[196:199], v[102:105]
	v_mfma_f32_16x16x32_bf16 v[98:101], v[138:141], v[196:199], v[98:101]
	v_mfma_f32_16x16x32_bf16 v[86:89], v[130:133], v[204:207], v[86:89]
	v_mfma_f32_16x16x32_bf16 v[82:85], v[138:141], v[204:207], v[82:85]
	v_mfma_f32_16x16x32_bf16 v[126:129], v[134:137], v[166:169], v[126:129]
	v_mfma_f32_16x16x32_bf16 v[122:125], v[142:145], v[166:169], v[122:125]
	v_mfma_f32_16x16x32_bf16 v[118:121], v[134:137], v[174:177], v[118:121]
	v_mfma_f32_16x16x32_bf16 v[114:117], v[142:145], v[174:177], v[114:117]
	v_mfma_f32_16x16x32_bf16 v[102:105], v[134:137], v[200:203], v[102:105]
	v_mfma_f32_16x16x32_bf16 v[98:101], v[142:145], v[200:203], v[98:101]
	v_mfma_f32_16x16x32_bf16 v[86:89], v[134:137], v[208:211], v[86:89]
	v_mfma_f32_16x16x32_bf16 v[82:85], v[142:145], v[208:211], v[82:85]
	s_setprio 0
	s_setprio 1
	v_mfma_f32_16x16x32_bf16 v[110:113], v[146:149], v[162:165], v[110:113]
	v_mfma_f32_16x16x32_bf16 v[106:109], v[154:157], v[162:165], v[106:109]
	v_mfma_f32_16x16x32_bf16 v[94:97], v[146:149], v[170:173], v[94:97]
	v_mfma_f32_16x16x32_bf16 v[90:93], v[154:157], v[170:173], v[90:93]
	v_mfma_f32_16x16x32_bf16 v[78:81], v[146:149], v[196:199], v[78:81]
	v_mfma_f32_16x16x32_bf16 v[74:77], v[154:157], v[196:199], v[74:77]
	v_mfma_f32_16x16x32_bf16 v[70:73], v[146:149], v[204:207], v[70:73]
	v_mfma_f32_16x16x32_bf16 v[66:69], v[154:157], v[204:207], v[66:69]
	v_mfma_f32_16x16x32_bf16 v[110:113], v[150:153], v[166:169], v[110:113]
	v_mfma_f32_16x16x32_bf16 v[106:109], v[158:161], v[166:169], v[106:109]
	v_mfma_f32_16x16x32_bf16 v[94:97], v[150:153], v[174:177], v[94:97]
	v_mfma_f32_16x16x32_bf16 v[90:93], v[158:161], v[174:177], v[90:93]
	v_mfma_f32_16x16x32_bf16 v[78:81], v[150:153], v[200:203], v[78:81]
	v_mfma_f32_16x16x32_bf16 v[74:77], v[158:161], v[200:203], v[74:77]
	v_mfma_f32_16x16x32_bf16 v[70:73], v[150:153], v[208:211], v[70:73]
	v_mfma_f32_16x16x32_bf16 v[66:69], v[158:161], v[208:211], v[66:69]
	s_setprio 0
	s_barrier
	s_add_i32 s50, s68, s63
	v_lshl_add_u64 v[212:213], v[212:213], 0, s[94:95]
	s_mov_b32 m0, s50
	ds_read_b128 v[162:165], v226 offset:49152
	ds_read_b128 v[166:169], v226 offset:50176
	ds_read_b128 v[170:173], v226 offset:51200
	ds_read_b128 v[174:177], v226 offset:52224
	ds_read_b128 v[196:199], v226 offset:53248
	ds_read_b128 v[200:203], v226 offset:54272
	ds_read_b128 v[204:207], v226 offset:55296
	ds_read_b128 v[208:211], v226 offset:56320
	global_load_lds_dwordx4 v[212:213], off
	v_lshl_add_u64 v[212:213], v[214:215], 0, s[94:95]
	s_add_i32 m0, s50, 0x2000
	s_add_i32 s50, s69, s63
	global_load_lds_dwordx4 v[212:213], off
	v_lshl_add_u64 v[212:213], v[216:217], 0, s[94:95]
	s_mov_b32 m0, s50
	s_nop 0
	global_load_lds_dwordx4 v[212:213], off
	v_lshl_add_u64 v[212:213], v[218:219], 0, s[94:95]
	s_add_i32 m0, s50, 0x2000
	s_nop 0
	global_load_lds_dwordx4 v[212:213], off
	v_lshl_add_u64 v[212:213], v[232:233], 0, s[94:95]
	s_mov_b32 m0, s87
	s_nop 0
	global_load_lds_dwordx4 v[212:213], off
	v_lshl_add_u64 v[212:213], v[234:235], 0, s[94:95]
	s_mov_b32 m0, s2
	s_nop 0
	global_load_lds_dwordx4 v[212:213], off
	s_waitcnt vmcnt(8)
	s_add_i32 s98, vcc_lo, -2
	s_cmp_lt_u32 s98, 16
	s_cbranch_scc0 .Lrk_dL_8_16
	s_cmp_lt_u32 s98, 8
	s_cbranch_scc0 .Lrk_dL_4_8
	s_cmp_lt_u32 s98, 4
	s_cbranch_scc0 .Lrk_dL_2_4
	s_cmp_lt_u32 s98, 2
	s_cbranch_scc0 .Lrk_dL_1_2
	v_pk_add_f32 v[62:63], v[62:63], v[240:241]
	v_pk_add_f32 v[64:65], v[64:65], v[242:243]
	s_branch .Lrk_joinL
